# unchecked attention tiles: QK split by key half so softmax of half 0 runs under QK MFMAs of half 1, PV starts right after QK
# speedup vs baseline: 1.0042x; 1.0042x over previous
.Lu884:
	s_add_u32 s72, s8, s0
	s_addc_u32 s73, s9, s1
	s_add_u32 m0, s74, 0x6000
	s_nop 0
	global_load_lds_dwordx4 v164, s[72:73]
	s_add_u32 m0, s74, 0x8000
	s_nop 0
	global_load_lds_dwordx4 v170, s[72:73]
	s_add_u32 m0, s74, 0xa000
	s_nop 0
	global_load_lds_dwordx4 v168, s[72:73]
	s_cmp_gt_u32 s57, s75
	s_cbranch_scc1 .Lu888
	ds_read_b128 v[146:149], v198
	ds_read_b128 v[150:153], v171
	ds_read_b128 v[246:249], v174
	ds_read_b128 v[250:253], v175
	ds_read_b128 v[180:183], v176
	ds_read_b128 v[184:187], v177
	s_waitcnt lgkmcnt(5)
	v_mfma_f32_32x32x16_bf16 v[82:97], v[146:149], v[98:101], v[210:225]
	ds_read_b128 v[146:149], v178
	s_waitcnt lgkmcnt(5)
	v_mfma_f32_32x32x16_bf16 v[82:97], v[150:153], v[102:105], v[82:97]
	ds_read_b128 v[150:153], v179
	s_waitcnt lgkmcnt(5)
	v_mfma_f32_32x32x16_bf16 v[82:97], v[246:249], v[106:109], v[82:97]
	ds_read_b128 v[246:249], v199
	s_waitcnt lgkmcnt(5)
	v_mfma_f32_32x32x16_bf16 v[82:97], v[250:253], v[110:113], v[82:97]
	ds_read_b128 v[250:253], v202
	s_waitcnt lgkmcnt(5)
	v_mfma_f32_32x32x16_bf16 v[82:97], v[180:183], v[122:125], v[82:97]
	ds_read_b128 v[180:183], v207
	s_waitcnt lgkmcnt(5)
	v_mfma_f32_32x32x16_bf16 v[82:97], v[184:187], v[114:117], v[82:97]
	ds_read_b128 v[184:187], v208
	s_waitcnt lgkmcnt(5)
	v_mfma_f32_32x32x16_bf16 v[82:97], v[146:149], v[118:121], v[82:97]
	ds_read_b128 v[146:149], v198 offset:8192
	s_waitcnt lgkmcnt(5)
	v_mfma_f32_32x32x16_bf16 v[82:97], v[150:153], v[126:129], v[82:97]
	ds_read_b128 v[150:153], v171 offset:8192
	s_waitcnt lgkmcnt(5)
	v_mfma_f32_32x32x16_bf16 v[82:97], v[246:249], v[130:133], v[82:97]
	ds_read_b128 v[246:249], v174 offset:8192
	s_waitcnt lgkmcnt(5)
	v_mfma_f32_32x32x16_bf16 v[82:97], v[250:253], v[134:137], v[82:97]
	ds_read_b128 v[250:253], v175 offset:8192
	s_waitcnt lgkmcnt(5)
	v_mfma_f32_32x32x16_bf16 v[82:97], v[180:183], v[138:141], v[82:97]
	ds_read_b128 v[180:183], v176 offset:8192
	s_waitcnt lgkmcnt(5)
	v_mfma_f32_32x32x16_bf16 v[82:97], v[184:187], v[142:145], v[82:97]
	ds_read_b128 v[184:187], v177 offset:8192
	ds_read_b64_tr_b16 v[238:239], v188 offset:0
	ds_read_b64_tr_b16 v[240:241], v189 offset:0
	s_waitcnt lgkmcnt(7)
	v_mfma_f32_32x32x16_bf16 v[66:81], v[146:149], v[98:101], v[210:225]
	ds_read_b128 v[146:149], v178 offset:8192
	ds_read_b64_tr_b16 v[234:235], v192 offset:0
	ds_read_b64_tr_b16 v[236:237], v193 offset:0
	s_waitcnt lgkmcnt(9)
	v_mfma_f32_32x32x16_bf16 v[66:81], v[150:153], v[102:105], v[66:81]
	ds_read_b128 v[150:153], v179 offset:8192
	ds_read_b64_tr_b16 v[230:231], v194 offset:0
	ds_read_b64_tr_b16 v[232:233], v195 offset:0
	s_waitcnt lgkmcnt(11)
	v_mfma_f32_32x32x16_bf16 v[66:81], v[246:249], v[106:109], v[66:81]
	ds_read_b128 v[246:249], v199 offset:4096
	ds_read_b64_tr_b16 v[226:227], v196 offset:0
	ds_read_b64_tr_b16 v[228:229], v197 offset:0
	s_waitcnt lgkmcnt(13)
	v_mfma_f32_32x32x16_bf16 v[66:81], v[250:253], v[110:113], v[66:81]
	ds_read_b128 v[250:253], v202 offset:4096
	v_exp_f32_e32 v82, v82
	v_exp_f32_e32 v83, v83
	v_exp_f32_e32 v84, v84
	v_add_f32_e32 v173, v173, v82
	v_exp_f32_e32 v85, v85
	s_waitcnt lgkmcnt(13)
	v_mfma_f32_32x32x16_bf16 v[66:81], v[180:183], v[122:125], v[66:81]
	ds_read_b128 v[180:183], v207 offset:4096
	v_mov_b32_e32 v242, v83
	v_cvt_pk_bf16_f32 v82, v82, v83
	v_exp_f32_e32 v86, v86
	v_add_f32_e32 v173, v173, v84
	v_exp_f32_e32 v87, v87
	s_waitcnt lgkmcnt(13)
	v_mfma_f32_32x32x16_bf16 v[66:81], v[184:187], v[114:117], v[66:81]
	ds_read_b128 v[184:187], v208 offset:4096
	v_add_f32_e32 v242, v242, v85
	v_cvt_pk_bf16_f32 v83, v84, v85
	v_exp_f32_e32 v88, v88
	v_add_f32_e32 v173, v173, v86
	v_exp_f32_e32 v89, v89
	s_waitcnt lgkmcnt(11)
	v_mfma_f32_32x32x16_bf16 v[66:81], v[146:149], v[118:121], v[66:81]
	v_add_f32_e32 v242, v242, v87
	v_cvt_pk_bf16_f32 v84, v86, v87
	v_add_f32_e32 v173, v173, v88
	v_add_f32_e32 v242, v242, v89
	v_cvt_pk_bf16_f32 v85, v88, v89
	s_waitcnt lgkmcnt(8)
	v_mfma_f32_32x32x16_bf16 v[66:81], v[150:153], v[126:129], v[66:81]
	v_exp_f32_e32 v90, v90
	v_exp_f32_e32 v91, v91
	v_exp_f32_e32 v92, v92
	v_add_f32_e32 v173, v173, v90
	s_waitcnt lgkmcnt(5)
	v_mfma_f32_32x32x16_bf16 v[66:81], v[246:249], v[130:133], v[66:81]
	v_exp_f32_e32 v93, v93
	v_add_f32_e32 v242, v242, v91
	v_cvt_pk_bf16_f32 v90, v90, v91
	v_exp_f32_e32 v94, v94
	s_waitcnt lgkmcnt(2)
	v_mfma_f32_32x32x16_bf16 v[66:81], v[250:253], v[134:137], v[66:81]
	v_add_f32_e32 v173, v173, v92
	v_exp_f32_e32 v95, v95
	v_add_f32_e32 v242, v242, v93
	v_cvt_pk_bf16_f32 v91, v92, v93
	s_waitcnt lgkmcnt(1)
	v_mfma_f32_32x32x16_bf16 v[66:81], v[180:183], v[138:141], v[66:81]
	v_exp_f32_e32 v96, v96
	v_add_f32_e32 v173, v173, v94
	v_exp_f32_e32 v97, v97
	v_add_f32_e32 v242, v242, v95
	s_waitcnt lgkmcnt(0)
	v_mfma_f32_32x32x16_bf16 v[66:81], v[184:187], v[142:145], v[66:81]
	v_cvt_pk_bf16_f32 v92, v94, v95
	v_add_f32_e32 v173, v173, v96
	v_add_f32_e32 v242, v242, v97
	v_cvt_pk_bf16_f32 v93, v96, v97
	ds_read_b64_tr_b16 v[158:159], v188 offset:0x1000
	ds_read_b64_tr_b16 v[160:161], v189 offset:0x1000
	ds_read_b64_tr_b16 v[154:155], v192 offset:0x1000
	ds_read_b64_tr_b16 v[156:157], v193 offset:0x1000
	ds_read_b64_tr_b16 v[150:151], v194 offset:0x1000
	ds_read_b64_tr_b16 v[152:153], v195 offset:0x1000
	ds_read_b64_tr_b16 v[146:147], v196 offset:0x1000
	ds_read_b64_tr_b16 v[148:149], v197 offset:0x1000
	v_mfma_f32_32x32x16_bf16 v[50:65], v[238:241], v[82:85], v[50:65]
	v_mfma_f32_32x32x16_bf16 v[34:49], v[234:237], v[82:85], v[34:49]
	v_mfma_f32_32x32x16_bf16 v[18:33], v[230:233], v[82:85], v[18:33]
	v_mfma_f32_32x32x16_bf16 v[2:17], v[226:229], v[82:85], v[2:17]
	ds_read_b64_tr_b16 v[238:239], v188 offset:0x2000
	ds_read_b64_tr_b16 v[240:241], v189 offset:0x2000
	ds_read_b64_tr_b16 v[234:235], v192 offset:0x2000
	ds_read_b64_tr_b16 v[236:237], v193 offset:0x2000
	ds_read_b64_tr_b16 v[230:231], v194 offset:0x2000
	ds_read_b64_tr_b16 v[232:233], v195 offset:0x2000
	ds_read_b64_tr_b16 v[226:227], v196 offset:0x2000
	ds_read_b64_tr_b16 v[228:229], v197 offset:0x2000
	s_waitcnt lgkmcnt(8)
	v_mfma_f32_32x32x16_bf16 v[50:65], v[158:161], v[90:93], v[50:65]
	v_exp_f32_e32 v66, v66
	v_exp_f32_e32 v67, v67
	v_exp_f32_e32 v68, v68
	v_add_f32_e32 v173, v173, v66
	v_exp_f32_e32 v69, v69
	v_mfma_f32_32x32x16_bf16 v[34:49], v[154:157], v[90:93], v[34:49]
	v_add_f32_e32 v242, v242, v67
	v_cvt_pk_bf16_f32 v66, v66, v67
	v_exp_f32_e32 v70, v70
	v_add_f32_e32 v173, v173, v68
	v_exp_f32_e32 v71, v71
	v_mfma_f32_32x32x16_bf16 v[18:33], v[150:153], v[90:93], v[18:33]
	v_add_f32_e32 v242, v242, v69
	v_cvt_pk_bf16_f32 v67, v68, v69
	v_exp_f32_e32 v72, v72
	v_add_f32_e32 v173, v173, v70
	v_exp_f32_e32 v73, v73
	v_mfma_f32_32x32x16_bf16 v[2:17], v[146:149], v[90:93], v[2:17]
	v_add_f32_e32 v242, v242, v71
	v_cvt_pk_bf16_f32 v68, v70, v71
	v_add_f32_e32 v173, v173, v72
	v_add_f32_e32 v242, v242, v73
	v_cvt_pk_bf16_f32 v69, v72, v73
	ds_read_b64_tr_b16 v[158:159], v188 offset:0x3000
	ds_read_b64_tr_b16 v[160:161], v189 offset:0x3000
	ds_read_b64_tr_b16 v[154:155], v192 offset:0x3000
	ds_read_b64_tr_b16 v[156:157], v193 offset:0x3000
	ds_read_b64_tr_b16 v[150:151], v194 offset:0x3000
	ds_read_b64_tr_b16 v[152:153], v195 offset:0x3000
	ds_read_b64_tr_b16 v[146:147], v196 offset:0x3000
	ds_read_b64_tr_b16 v[148:149], v197 offset:0x3000
	s_waitcnt lgkmcnt(8)
	v_mfma_f32_32x32x16_bf16 v[50:65], v[238:241], v[66:69], v[50:65]
	v_exp_f32_e32 v74, v74
	v_exp_f32_e32 v75, v75
	v_exp_f32_e32 v76, v76
	v_add_f32_e32 v173, v173, v74
	v_exp_f32_e32 v77, v77
	v_mfma_f32_32x32x16_bf16 v[34:49], v[234:237], v[66:69], v[34:49]
	v_add_f32_e32 v242, v242, v75
	v_cvt_pk_bf16_f32 v74, v74, v75
	v_exp_f32_e32 v78, v78
	v_add_f32_e32 v173, v173, v76
	v_exp_f32_e32 v79, v79
	v_mfma_f32_32x32x16_bf16 v[18:33], v[230:233], v[66:69], v[18:33]
	v_add_f32_e32 v242, v242, v77
	v_cvt_pk_bf16_f32 v75, v76, v77
	v_exp_f32_e32 v80, v80
	v_add_f32_e32 v173, v173, v78
	v_exp_f32_e32 v81, v81
	v_mfma_f32_32x32x16_bf16 v[2:17], v[226:229], v[66:69], v[2:17]
	v_add_f32_e32 v242, v242, v79
	v_cvt_pk_bf16_f32 v76, v78, v79
	v_add_f32_e32 v173, v173, v80
	v_add_f32_e32 v242, v242, v81
	v_cvt_pk_bf16_f32 v77, v80, v81
	s_waitcnt lgkmcnt(0)
	v_add_f32_e32 v173, v173, v242
	v_mfma_f32_32x32x16_bf16 v[50:65], v[158:161], v[74:77], v[50:65]
	v_mfma_f32_32x32x16_bf16 v[34:49], v[154:157], v[74:77], v[34:49]
	v_mfma_f32_32x32x16_bf16 v[18:33], v[150:153], v[74:77], v[18:33]
	v_mfma_f32_32x32x16_bf16 v[2:17], v[146:149], v[74:77], v[2:17]

.Lu890:
	s_cmp_ge_u32 s57, s75
	s_cbranch_scc1 .Lu883
	ds_read_b128 v[146:149], v198 offset:24576
	ds_read_b128 v[150:153], v171 offset:24576
	ds_read_b128 v[246:249], v174 offset:24576
	ds_read_b128 v[250:253], v175 offset:24576
	ds_read_b128 v[180:183], v176 offset:24576
	ds_read_b128 v[184:187], v177 offset:24576
	s_waitcnt lgkmcnt(5)
	v_mfma_f32_32x32x16_bf16 v[82:97], v[146:149], v[98:101], v[210:225]
	ds_read_b128 v[146:149], v178 offset:24576
	s_waitcnt lgkmcnt(5)
	v_mfma_f32_32x32x16_bf16 v[82:97], v[150:153], v[102:105], v[82:97]
	ds_read_b128 v[150:153], v179 offset:24576
	s_waitcnt lgkmcnt(5)
	v_mfma_f32_32x32x16_bf16 v[82:97], v[246:249], v[106:109], v[82:97]
	ds_read_b128 v[246:249], v199 offset:24576
	s_waitcnt lgkmcnt(5)
	v_mfma_f32_32x32x16_bf16 v[82:97], v[250:253], v[110:113], v[82:97]
	ds_read_b128 v[250:253], v202 offset:24576
	s_waitcnt lgkmcnt(5)
	v_mfma_f32_32x32x16_bf16 v[82:97], v[180:183], v[122:125], v[82:97]
	ds_read_b128 v[180:183], v207 offset:24576
	s_waitcnt lgkmcnt(5)
	v_mfma_f32_32x32x16_bf16 v[82:97], v[184:187], v[114:117], v[82:97]
	ds_read_b128 v[184:187], v208 offset:24576
	s_waitcnt lgkmcnt(5)
	v_mfma_f32_32x32x16_bf16 v[82:97], v[146:149], v[118:121], v[82:97]
	ds_read_b128 v[146:149], v198 offset:32768
	s_waitcnt lgkmcnt(5)
	v_mfma_f32_32x32x16_bf16 v[82:97], v[150:153], v[126:129], v[82:97]
	ds_read_b128 v[150:153], v171 offset:32768
	s_waitcnt lgkmcnt(5)
	v_mfma_f32_32x32x16_bf16 v[82:97], v[246:249], v[130:133], v[82:97]
	ds_read_b128 v[246:249], v174 offset:32768
	s_waitcnt lgkmcnt(5)
	v_mfma_f32_32x32x16_bf16 v[82:97], v[250:253], v[134:137], v[82:97]
	ds_read_b128 v[250:253], v175 offset:32768
	s_waitcnt lgkmcnt(5)
	v_mfma_f32_32x32x16_bf16 v[82:97], v[180:183], v[138:141], v[82:97]
	ds_read_b128 v[180:183], v176 offset:32768
	s_waitcnt lgkmcnt(5)
	v_mfma_f32_32x32x16_bf16 v[82:97], v[184:187], v[142:145], v[82:97]
	ds_read_b128 v[184:187], v177 offset:32768
	ds_read_b64_tr_b16 v[238:239], v188 offset:0x6000
	ds_read_b64_tr_b16 v[240:241], v189 offset:0x6000
	s_waitcnt lgkmcnt(7)
	v_mfma_f32_32x32x16_bf16 v[66:81], v[146:149], v[98:101], v[210:225]
	ds_read_b128 v[146:149], v178 offset:32768
	ds_read_b64_tr_b16 v[234:235], v192 offset:0x6000
	ds_read_b64_tr_b16 v[236:237], v193 offset:0x6000
	s_waitcnt lgkmcnt(9)
	v_mfma_f32_32x32x16_bf16 v[66:81], v[150:153], v[102:105], v[66:81]
	ds_read_b128 v[150:153], v179 offset:32768
	ds_read_b64_tr_b16 v[230:231], v194 offset:0x6000
	ds_read_b64_tr_b16 v[232:233], v195 offset:0x6000
	s_waitcnt lgkmcnt(11)
	v_mfma_f32_32x32x16_bf16 v[66:81], v[246:249], v[106:109], v[66:81]
	ds_read_b128 v[246:249], v199 offset:28672
	ds_read_b64_tr_b16 v[226:227], v196 offset:0x6000
	ds_read_b64_tr_b16 v[228:229], v197 offset:0x6000
	s_waitcnt lgkmcnt(13)
	v_mfma_f32_32x32x16_bf16 v[66:81], v[250:253], v[110:113], v[66:81]
	ds_read_b128 v[250:253], v202 offset:28672
	v_exp_f32_e32 v82, v82
	v_exp_f32_e32 v83, v83
	v_exp_f32_e32 v84, v84
	v_add_f32_e32 v173, v173, v82
	v_exp_f32_e32 v85, v85
	s_waitcnt lgkmcnt(13)
	v_mfma_f32_32x32x16_bf16 v[66:81], v[180:183], v[122:125], v[66:81]
	ds_read_b128 v[180:183], v207 offset:28672
	v_mov_b32_e32 v242, v83
	v_cvt_pk_bf16_f32 v82, v82, v83
	v_exp_f32_e32 v86, v86
	v_add_f32_e32 v173, v173, v84
	v_exp_f32_e32 v87, v87
	s_waitcnt lgkmcnt(13)
	v_mfma_f32_32x32x16_bf16 v[66:81], v[184:187], v[114:117], v[66:81]
	ds_read_b128 v[184:187], v208 offset:28672
	v_add_f32_e32 v242, v242, v85
	v_cvt_pk_bf16_f32 v83, v84, v85
	v_exp_f32_e32 v88, v88
	v_add_f32_e32 v173, v173, v86
	v_exp_f32_e32 v89, v89
	s_waitcnt lgkmcnt(11)
	v_mfma_f32_32x32x16_bf16 v[66:81], v[146:149], v[118:121], v[66:81]
	v_add_f32_e32 v242, v242, v87
	v_cvt_pk_bf16_f32 v84, v86, v87
	v_add_f32_e32 v173, v173, v88
	v_add_f32_e32 v242, v242, v89
	v_cvt_pk_bf16_f32 v85, v88, v89
	s_waitcnt lgkmcnt(8)
	v_mfma_f32_32x32x16_bf16 v[66:81], v[150:153], v[126:129], v[66:81]
	v_exp_f32_e32 v90, v90
	v_exp_f32_e32 v91, v91
	v_exp_f32_e32 v92, v92
	v_add_f32_e32 v173, v173, v90
	s_waitcnt lgkmcnt(5)
	v_mfma_f32_32x32x16_bf16 v[66:81], v[246:249], v[130:133], v[66:81]
	v_exp_f32_e32 v93, v93
	v_add_f32_e32 v242, v242, v91
	v_cvt_pk_bf16_f32 v90, v90, v91
	v_exp_f32_e32 v94, v94
	s_waitcnt lgkmcnt(2)
	v_mfma_f32_32x32x16_bf16 v[66:81], v[250:253], v[134:137], v[66:81]
	v_add_f32_e32 v173, v173, v92
	v_exp_f32_e32 v95, v95
	v_add_f32_e32 v242, v242, v93
	v_cvt_pk_bf16_f32 v91, v92, v93
	s_waitcnt lgkmcnt(1)
	v_mfma_f32_32x32x16_bf16 v[66:81], v[180:183], v[138:141], v[66:81]
	v_exp_f32_e32 v96, v96
	v_add_f32_e32 v173, v173, v94
	v_exp_f32_e32 v97, v97
	v_add_f32_e32 v242, v242, v95
	s_waitcnt lgkmcnt(0)
	v_mfma_f32_32x32x16_bf16 v[66:81], v[184:187], v[142:145], v[66:81]
	v_cvt_pk_bf16_f32 v92, v94, v95
	v_add_f32_e32 v173, v173, v96
	v_add_f32_e32 v242, v242, v97
	v_cvt_pk_bf16_f32 v93, v96, v97
	ds_read_b64_tr_b16 v[158:159], v188 offset:0x7000
	ds_read_b64_tr_b16 v[160:161], v189 offset:0x7000
	ds_read_b64_tr_b16 v[154:155], v192 offset:0x7000
	ds_read_b64_tr_b16 v[156:157], v193 offset:0x7000
	ds_read_b64_tr_b16 v[150:151], v194 offset:0x7000
	ds_read_b64_tr_b16 v[152:153], v195 offset:0x7000
	ds_read_b64_tr_b16 v[146:147], v196 offset:0x7000
	ds_read_b64_tr_b16 v[148:149], v197 offset:0x7000
	v_mfma_f32_32x32x16_bf16 v[50:65], v[238:241], v[82:85], v[50:65]
	v_mfma_f32_32x32x16_bf16 v[34:49], v[234:237], v[82:85], v[34:49]
	v_mfma_f32_32x32x16_bf16 v[18:33], v[230:233], v[82:85], v[18:33]
	v_mfma_f32_32x32x16_bf16 v[2:17], v[226:229], v[82:85], v[2:17]
	ds_read_b64_tr_b16 v[238:239], v188 offset:0x8000
	ds_read_b64_tr_b16 v[240:241], v189 offset:0x8000
	ds_read_b64_tr_b16 v[234:235], v192 offset:0x8000
	ds_read_b64_tr_b16 v[236:237], v193 offset:0x8000
	ds_read_b64_tr_b16 v[230:231], v194 offset:0x8000
	ds_read_b64_tr_b16 v[232:233], v195 offset:0x8000
	ds_read_b64_tr_b16 v[226:227], v196 offset:0x8000
	ds_read_b64_tr_b16 v[228:229], v197 offset:0x8000
	s_waitcnt lgkmcnt(8)
	v_mfma_f32_32x32x16_bf16 v[50:65], v[158:161], v[90:93], v[50:65]
	v_exp_f32_e32 v66, v66
	v_exp_f32_e32 v67, v67
	v_exp_f32_e32 v68, v68
	v_add_f32_e32 v173, v173, v66
	v_exp_f32_e32 v69, v69
	v_mfma_f32_32x32x16_bf16 v[34:49], v[154:157], v[90:93], v[34:49]
	v_add_f32_e32 v242, v242, v67
	v_cvt_pk_bf16_f32 v66, v66, v67
	v_exp_f32_e32 v70, v70
	v_add_f32_e32 v173, v173, v68
	v_exp_f32_e32 v71, v71
	v_mfma_f32_32x32x16_bf16 v[18:33], v[150:153], v[90:93], v[18:33]
	v_add_f32_e32 v242, v242, v69
	v_cvt_pk_bf16_f32 v67, v68, v69
	v_exp_f32_e32 v72, v72
	v_add_f32_e32 v173, v173, v70
	v_exp_f32_e32 v73, v73
	v_mfma_f32_32x32x16_bf16 v[2:17], v[146:149], v[90:93], v[2:17]
	v_add_f32_e32 v242, v242, v71
	v_cvt_pk_bf16_f32 v68, v70, v71
	v_add_f32_e32 v173, v173, v72
	v_add_f32_e32 v242, v242, v73
	v_cvt_pk_bf16_f32 v69, v72, v73
	ds_read_b64_tr_b16 v[158:159], v188 offset:0x9000
	ds_read_b64_tr_b16 v[160:161], v189 offset:0x9000
	ds_read_b64_tr_b16 v[154:155], v192 offset:0x9000
	ds_read_b64_tr_b16 v[156:157], v193 offset:0x9000
	ds_read_b64_tr_b16 v[150:151], v194 offset:0x9000
	ds_read_b64_tr_b16 v[152:153], v195 offset:0x9000
	ds_read_b64_tr_b16 v[146:147], v196 offset:0x9000
	ds_read_b64_tr_b16 v[148:149], v197 offset:0x9000
	s_waitcnt lgkmcnt(8)
	v_mfma_f32_32x32x16_bf16 v[50:65], v[238:241], v[66:69], v[50:65]
	v_exp_f32_e32 v74, v74
	v_exp_f32_e32 v75, v75
	v_exp_f32_e32 v76, v76
	v_add_f32_e32 v173, v173, v74
	v_exp_f32_e32 v77, v77
	v_mfma_f32_32x32x16_bf16 v[34:49], v[234:237], v[66:69], v[34:49]
	v_add_f32_e32 v242, v242, v75
	v_cvt_pk_bf16_f32 v74, v74, v75
	v_exp_f32_e32 v78, v78
	v_add_f32_e32 v173, v173, v76
	v_exp_f32_e32 v79, v79
	v_mfma_f32_32x32x16_bf16 v[18:33], v[230:233], v[66:69], v[18:33]
	v_add_f32_e32 v242, v242, v77
	v_cvt_pk_bf16_f32 v75, v76, v77
	v_exp_f32_e32 v80, v80
	v_add_f32_e32 v173, v173, v78
	v_exp_f32_e32 v81, v81
	v_mfma_f32_32x32x16_bf16 v[2:17], v[226:229], v[66:69], v[2:17]
	v_add_f32_e32 v242, v242, v79
	v_cvt_pk_bf16_f32 v76, v78, v79
	v_add_f32_e32 v173, v173, v80
	v_add_f32_e32 v242, v242, v81
	v_cvt_pk_bf16_f32 v77, v80, v81
	s_waitcnt lgkmcnt(0)
	v_add_f32_e32 v173, v173, v242
	v_mfma_f32_32x32x16_bf16 v[50:65], v[158:161], v[74:77], v[50:65]
	v_mfma_f32_32x32x16_bf16 v[34:49], v[154:157], v[74:77], v[34:49]
	v_mfma_f32_32x32x16_bf16 v[18:33], v[150:153], v[74:77], v[18:33]
	v_mfma_f32_32x32x16_bf16 v[2:17], v[146:149], v[74:77], v[2:17]
	s_branch .Lu883
